# phase_post rotary blocks: the per-lane sign word and the rotating-lane mask are computed once per row instead of in each of the 43 blocks
# baseline (speedup 1.0000x reference)
.LBB0_644:
	v_ashrrev_i32_e32 v43, 31, v42
	v_mov_b32_e32 v209, 0x80000000
	v_cmp_gt_i32_e64 s[100:101], 1, v16
	s_nop 1
	v_cndmask_b32_e64 v208, 0, v209, s[100:101]
	v_cmp_gt_i32_e64 s[100:101], 2, v16
	v_lshlrev_b64 v[200:201], 12, v[42:43]
	v_lshl_add_u64 v[200:201], v[48:49], 0, v[200:201]
	global_load_dwordx4 v[176:179], v[200:201], off
	global_load_dwordx4 v[180:183], v[200:201], off offset:16
	v_lshlrev_b64 v[202:203], 8, v[42:43]
	v_lshl_add_u64 v[202:203], v[50:51], 0, v[202:203]
	global_load_dwordx4 v[184:187], v[202:203], off
	global_load_dwordx4 v[188:191], v[202:203], off offset:16
	v_lshlrev_b64 v[204:205], 10, v[42:43]
	v_lshl_add_u64 v[204:205], v[52:53], 0, v[204:205]
	global_load_dwordx4 v[192:195], v[204:205], off
	v_lshlrev_b64 v[206:207], 7, v[42:43]
	v_lshl_add_u64 v[206:207], v[54:55], 0, v[206:207]
	global_load_dwordx4 v[196:199], v[206:207], off
	s_and_saveexec_b64 s[0:1], vcc
	s_cbranch_execz .LBB0_646
	v_readlane_b32 s64, v253, 22
	v_readlane_b32 s66, v253, 24
	v_readlane_b32 s67, v253, 25
	v_readlane_b32 s65, v253, 23
	v_readlane_b32 s68, v253, 26
	v_lshl_add_u64 v[0:1], v[42:43], 2, s[66:67]
	global_load_dword v2, v[0:1], off
	s_nop 0
	global_load_dwordx2 v[0:1], v[46:47], off
	v_readlane_b32 s69, v253, 27
	v_readlane_b32 s70, v253, 28
	v_readlane_b32 s71, v253, 29
	v_readlane_b32 s72, v253, 30
	v_readlane_b32 s73, v253, 31
	v_readlane_b32 s74, v253, 32
	v_readlane_b32 s75, v253, 33
	v_readlane_b32 s76, v253, 34
	v_readlane_b32 s77, v253, 35
	v_readlane_b32 s78, v253, 36
	v_readlane_b32 s79, v253, 37
	s_waitcnt vmcnt(0)
	v_cvt_f64_i32_e32 v[2:3], v2
	v_mul_f64 v[4:5], v[0:1], v[2:3]
	v_rndne_f64_e32 v[4:5], v[4:5]
	v_fma_f64 v[0:1], v[0:1], v[2:3], -v[4:5]
	v_cvt_f32_f64_e32 v1, v[0:1]
	v_cos_f32_e32 v0, v1
	v_sin_f32_e32 v1, v1
	v_add_u32_e32 v2, v108, v44
	ds_write_b64 v2, v[0:1]

.LBB0_652:
	s_or_b64 exec, exec, s[0:1]
	ds_bpermute_b32 v5, v45, v97
	s_waitcnt lgkmcnt(2)
	ds_read_b64 v[2:3], v108 offset:8
	s_and_saveexec_b64 s[22:23], s[100:101]
	v_mov_b32_e32 v6, v97
	s_waitcnt lgkmcnt(0)
	v_mov_b32_e32 v7, v3
	v_mov_b32_e32 v4, v2
	v_mul_f32_e32 v56, v97, v2
	v_xor_b32_e32 v210, v208, v6
	v_xor_b32_e32 v211, v208, v7
	v_pk_fma_f32 v[4:5], v[210:211], v[4:5], v[56:57] op_sel_hi:[1,1,0]
	s_nop 0
	v_mov_b32_e32 v97, v5
	s_or_b64 exec, exec, s[22:23]
	s_waitcnt lgkmcnt(1)
	ds_bpermute_b32 v5, v45, v94
	ds_read_b64 v[6:7], v108 offset:16
	s_and_saveexec_b64 s[22:23], s[100:101]
	v_mov_b32_e32 v56, v94
	s_waitcnt lgkmcnt(0)
	v_mov_b32_e32 v57, v7
	v_mov_b32_e32 v4, v6
	v_mul_f32_e32 v58, v7, v5
	v_xor_b32_e32 v210, v208, v58
	v_xor_b32_e32 v211, v208, v59
	v_pk_fma_f32 v[4:5], v[56:57], v[4:5], v[210:211] op_sel_hi:[1,1,0]
	s_nop 0
	v_mov_b32_e32 v94, v4
	s_or_b64 exec, exec, s[22:23]
	ds_bpermute_b32 v57, v45, v95
	s_waitcnt lgkmcnt(2)
	ds_read_b64 v[4:5], v108 offset:24
	s_and_saveexec_b64 s[22:23], s[100:101]
	v_mov_b32_e32 v58, v95
	s_waitcnt lgkmcnt(0)
	v_mov_b32_e32 v59, v5
	v_mov_b32_e32 v56, v4
	v_mul_f32_e32 v60, v5, v57
	v_xor_b32_e32 v210, v208, v60
	v_xor_b32_e32 v211, v208, v61
	v_pk_fma_f32 v[56:57], v[58:59], v[56:57], v[210:211] op_sel_hi:[1,1,0]
	s_nop 0
	v_mov_b32_e32 v95, v56
	s_or_b64 exec, exec, s[22:23]
	s_waitcnt lgkmcnt(1)
	ds_bpermute_b32 v57, v45, v92
	ds_read_b64 v[58:59], v108 offset:32
	s_and_saveexec_b64 s[22:23], s[100:101]
	v_mov_b32_e32 v60, v92
	s_waitcnt lgkmcnt(0)
	v_mov_b32_e32 v61, v59
	v_mov_b32_e32 v56, v58
	v_mul_f32_e32 v62, v59, v57
	v_xor_b32_e32 v210, v208, v62
	v_xor_b32_e32 v211, v208, v63
	v_pk_fma_f32 v[56:57], v[60:61], v[56:57], v[210:211] op_sel_hi:[1,1,0]
	s_nop 0
	v_mov_b32_e32 v92, v56
	s_or_b64 exec, exec, s[22:23]
	ds_bpermute_b32 v61, v45, v93
	s_waitcnt lgkmcnt(2)
	ds_read_b64 v[56:57], v108 offset:40
	s_and_saveexec_b64 s[22:23], s[100:101]
	v_mov_b32_e32 v62, v93
	s_waitcnt lgkmcnt(0)
	v_mov_b32_e32 v63, v57
	v_mov_b32_e32 v60, v56
	v_mul_f32_e32 v64, v57, v61
	v_xor_b32_e32 v210, v208, v64
	v_xor_b32_e32 v211, v208, v65
	v_pk_fma_f32 v[60:61], v[62:63], v[60:61], v[210:211] op_sel_hi:[1,1,0]
	s_nop 0
	v_mov_b32_e32 v93, v60
	s_or_b64 exec, exec, s[22:23]
	s_waitcnt lgkmcnt(1)
	ds_bpermute_b32 v61, v45, v90
	ds_read_b64 v[62:63], v108 offset:48
	s_and_saveexec_b64 s[22:23], s[100:101]
	v_mov_b32_e32 v64, v90
	s_waitcnt lgkmcnt(0)
	v_mov_b32_e32 v65, v63
	v_mov_b32_e32 v60, v62
	v_mul_f32_e32 v66, v63, v61
	v_xor_b32_e32 v210, v208, v66
	v_xor_b32_e32 v211, v208, v67
	v_pk_fma_f32 v[60:61], v[64:65], v[60:61], v[210:211] op_sel_hi:[1,1,0]
	s_nop 0
	v_mov_b32_e32 v90, v60
	s_or_b64 exec, exec, s[22:23]
	ds_bpermute_b32 v65, v45, v91
	s_waitcnt lgkmcnt(2)
	ds_read_b64 v[60:61], v108 offset:56
	s_and_saveexec_b64 s[22:23], s[100:101]
	v_mov_b32_e32 v66, v91
	s_waitcnt lgkmcnt(0)
	v_mov_b32_e32 v67, v61
	v_mov_b32_e32 v64, v60
	v_mul_f32_e32 v68, v61, v65
	v_xor_b32_e32 v210, v208, v68
	v_xor_b32_e32 v211, v208, v69
	v_pk_fma_f32 v[64:65], v[66:67], v[64:65], v[210:211] op_sel_hi:[1,1,0]
	s_nop 0
	v_mov_b32_e32 v91, v64
	s_or_b64 exec, exec, s[22:23]
	s_waitcnt lgkmcnt(1)
	ds_bpermute_b32 v65, v45, v88
	ds_read_b64 v[66:67], v108 offset:64
	s_and_saveexec_b64 s[22:23], s[100:101]
	v_mov_b32_e32 v68, v88
	s_waitcnt lgkmcnt(0)
	v_mov_b32_e32 v69, v67
	v_mov_b32_e32 v64, v66
	v_mul_f32_e32 v70, v67, v65
	v_xor_b32_e32 v210, v208, v70
	v_xor_b32_e32 v211, v208, v71
	v_pk_fma_f32 v[64:65], v[68:69], v[64:65], v[210:211] op_sel_hi:[1,1,0]
	s_nop 0
	v_mov_b32_e32 v88, v64
	s_or_b64 exec, exec, s[22:23]
	ds_bpermute_b32 v69, v45, v89
	s_waitcnt lgkmcnt(2)
	ds_read_b64 v[64:65], v108 offset:72
	s_and_saveexec_b64 s[22:23], s[100:101]
	v_mov_b32_e32 v70, v89
	s_waitcnt lgkmcnt(0)
	v_mov_b32_e32 v71, v65
	v_mov_b32_e32 v68, v64
	v_mul_f32_e32 v72, v65, v69
	v_xor_b32_e32 v210, v208, v72
	v_xor_b32_e32 v211, v208, v73
	v_pk_fma_f32 v[68:69], v[70:71], v[68:69], v[210:211] op_sel_hi:[1,1,0]
	s_nop 0
	v_mov_b32_e32 v89, v68
	s_or_b64 exec, exec, s[22:23]
	s_waitcnt lgkmcnt(1)
	ds_bpermute_b32 v69, v45, v86
	ds_read_b64 v[70:71], v108 offset:80
	s_and_saveexec_b64 s[22:23], s[100:101]
	v_mov_b32_e32 v72, v86
	s_waitcnt lgkmcnt(0)
	v_mov_b32_e32 v73, v71
	v_mov_b32_e32 v68, v70
	v_mul_f32_e32 v74, v71, v69
	v_xor_b32_e32 v210, v208, v74
	v_xor_b32_e32 v211, v208, v75
	v_pk_fma_f32 v[68:69], v[72:73], v[68:69], v[210:211] op_sel_hi:[1,1,0]
	s_nop 0
	v_mov_b32_e32 v86, v68
	s_or_b64 exec, exec, s[22:23]
	ds_bpermute_b32 v73, v45, v87
	s_waitcnt lgkmcnt(2)
	ds_read_b64 v[68:69], v108 offset:88
	s_and_saveexec_b64 s[22:23], s[100:101]
	v_mov_b32_e32 v74, v87
	s_waitcnt lgkmcnt(0)
	v_mov_b32_e32 v75, v69
	v_mov_b32_e32 v72, v68
	v_mul_f32_e32 v76, v69, v73
	v_xor_b32_e32 v210, v208, v76
	v_xor_b32_e32 v211, v208, v77
	v_pk_fma_f32 v[72:73], v[74:75], v[72:73], v[210:211] op_sel_hi:[1,1,0]
	s_nop 0
	v_mov_b32_e32 v87, v72
	s_or_b64 exec, exec, s[22:23]
	s_waitcnt lgkmcnt(1)
	ds_bpermute_b32 v73, v45, v84
	ds_read_b64 v[74:75], v108 offset:96
	s_and_saveexec_b64 s[22:23], s[100:101]
	v_mov_b32_e32 v76, v84
	s_waitcnt lgkmcnt(0)
	v_mov_b32_e32 v77, v75
	v_mov_b32_e32 v72, v74
	v_mul_f32_e32 v78, v75, v73
	v_xor_b32_e32 v210, v208, v78
	v_xor_b32_e32 v211, v208, v79
	v_pk_fma_f32 v[72:73], v[76:77], v[72:73], v[210:211] op_sel_hi:[1,1,0]
	s_nop 0
	v_mov_b32_e32 v84, v72
	s_or_b64 exec, exec, s[22:23]
	ds_bpermute_b32 v77, v45, v85
	s_waitcnt lgkmcnt(2)
	ds_read_b64 v[72:73], v108 offset:104
	s_and_saveexec_b64 s[22:23], s[100:101]
	v_mov_b32_e32 v78, v85
	s_waitcnt lgkmcnt(0)
	v_mov_b32_e32 v79, v73
	v_mov_b32_e32 v76, v72
	v_mul_f32_e32 v98, v73, v77
	v_xor_b32_e32 v210, v208, v98
	v_xor_b32_e32 v211, v208, v99
	v_pk_fma_f32 v[76:77], v[78:79], v[76:77], v[210:211] op_sel_hi:[1,1,0]
	s_nop 0
	v_mov_b32_e32 v85, v76
	s_or_b64 exec, exec, s[22:23]
	s_waitcnt lgkmcnt(1)
	ds_bpermute_b32 v77, v45, v82
	ds_read_b64 v[78:79], v108 offset:112
	s_and_saveexec_b64 s[22:23], s[100:101]
	v_mov_b32_e32 v98, v82
	s_waitcnt lgkmcnt(0)
	v_mov_b32_e32 v99, v79
	v_mov_b32_e32 v76, v78
	v_mul_f32_e32 v82, v79, v77
	v_xor_b32_e32 v210, v208, v82
	v_xor_b32_e32 v211, v208, v83
	v_pk_fma_f32 v[76:77], v[98:99], v[76:77], v[210:211] op_sel_hi:[1,1,0]
	s_nop 0
	v_mov_b32_e32 v82, v76
	s_or_b64 exec, exec, s[22:23]
	ds_bpermute_b32 v99, v45, v83
	s_waitcnt lgkmcnt(2)
	ds_read_b64 v[76:77], v108 offset:120
	s_and_saveexec_b64 s[22:23], s[100:101]
	v_mov_b32_e32 v100, v83
	s_waitcnt lgkmcnt(0)
	v_mov_b32_e32 v101, v77
	v_mov_b32_e32 v98, v76
	v_mul_f32_e32 v102, v77, v99
	v_xor_b32_e32 v210, v208, v102
	v_xor_b32_e32 v211, v208, v103
	v_pk_fma_f32 v[98:99], v[100:101], v[98:99], v[210:211] op_sel_hi:[1,1,0]
	s_nop 0
	v_mov_b32_e32 v83, v98
	s_or_b64 exec, exec, s[22:23]
	v_cvt_pk_bf16_f32 v96, v96, v97
	v_cvt_pk_bf16_f32 v97, v94, v95
	v_cvt_pk_bf16_f32 v98, v92, v93
	s_waitcnt lgkmcnt(1)
	v_cvt_pk_bf16_f32 v99, v90, v91
	v_cvt_pk_bf16_f32 v88, v88, v89
	v_cvt_pk_bf16_f32 v89, v86, v87
	v_cvt_pk_bf16_f32 v90, v84, v85
	v_cvt_pk_bf16_f32 v91, v82, v83
	global_store_dwordx4 v[80:81], v[96:99], off
	global_store_dwordx4 v[80:81], v[88:91], off offset:16
	v_lshlrev_b64 v[80:81], 8, v[42:43]
	v_lshl_add_u64 v[80:81], v[50:51], 0, v[80:81]
	v_mov_b32_e32 v90, 0
	v_mov_b32_e32 v91, 0
	v_mov_b32_e32 v82, 0
	v_mov_b32_e32 v83, 0
	v_mov_b32_e32 v84, 0
	v_mov_b32_e32 v85, 0
	v_mov_b32_e32 v86, 0
	v_mov_b32_e32 v87, 0
	v_mov_b32_e32 v88, 0
	v_mov_b32_e32 v89, 0
	v_mov_b32_e32 v100, 0
	v_mov_b32_e32 v101, 0
	v_mov_b32_e32 v102, 0
	v_mov_b32_e32 v103, 0
	v_mov_b32_e32 v104, 0
	v_mov_b32_e32 v105, 0
	s_and_saveexec_b64 s[0:1], s[4:5]
	s_cbranch_execz .LBB0_744
	v_mov_b32_e32 v84, v184
	v_mov_b32_e32 v85, v185
	v_mov_b32_e32 v86, v186
	v_mov_b32_e32 v87, v187
	v_mov_b32_e32 v92, v188
	v_mov_b32_e32 v93, v189
	v_mov_b32_e32 v94, v190
	v_mov_b32_e32 v95, v191
	v_lshlrev_b32_e32 v90, 16, v84
	v_and_b32_e32 v91, 0xffff0000, v84
	v_lshlrev_b32_e32 v82, 16, v85
	v_and_b32_e32 v83, 0xffff0000, v85
	v_lshlrev_b32_e32 v84, 16, v86
	v_and_b32_e32 v85, 0xffff0000, v86
	v_lshlrev_b32_e32 v86, 16, v87
	v_and_b32_e32 v87, 0xffff0000, v87
	v_lshlrev_b32_e32 v88, 16, v92
	v_and_b32_e32 v89, 0xffff0000, v92
	v_lshlrev_b32_e32 v100, 16, v93
	v_and_b32_e32 v101, 0xffff0000, v93
	v_lshlrev_b32_e32 v102, 16, v94
	v_and_b32_e32 v103, 0xffff0000, v94
	v_lshlrev_b32_e32 v104, 16, v95
	v_and_b32_e32 v105, 0xffff0000, v95

.LBB0_750:
	s_or_b64 exec, exec, s[0:1]
	ds_bpermute_b32 v1, v45, v97
	s_and_saveexec_b64 s[22:23], s[100:101]
	v_mov_b32_e32 v0, v97
	v_mul_f32_e32 v98, v2, v97
	s_waitcnt lgkmcnt(0)
	v_xor_b32_e32 v210, v208, v2
	v_xor_b32_e32 v211, v208, v3
	v_pk_fma_f32 v[0:1], v[210:211], v[0:1], v[98:99] op_sel_hi:[1,1,0]
	s_nop 0
	v_mov_b32_e32 v97, v1
	s_or_b64 exec, exec, s[22:23]
	s_waitcnt lgkmcnt(0)
	ds_bpermute_b32 v1, v45, v94
	s_and_saveexec_b64 s[22:23], s[100:101]
	v_mov_b32_e32 v0, v94
	s_waitcnt lgkmcnt(0)
	v_mul_f32_e32 v2, v7, v1
	v_xor_b32_e32 v210, v208, v2
	v_xor_b32_e32 v211, v208, v3
	v_pk_fma_f32 v[0:1], v[6:7], v[0:1], v[210:211] op_sel_hi:[1,1,0]
	s_nop 0
	v_mov_b32_e32 v94, v0
	s_or_b64 exec, exec, s[22:23]
	s_waitcnt lgkmcnt(0)
	ds_bpermute_b32 v1, v45, v95
	s_and_saveexec_b64 s[22:23], s[100:101]
	v_mov_b32_e32 v0, v95
	s_waitcnt lgkmcnt(0)
	v_mul_f32_e32 v2, v5, v1
	v_xor_b32_e32 v210, v208, v2
	v_xor_b32_e32 v211, v208, v3
	v_pk_fma_f32 v[0:1], v[4:5], v[0:1], v[210:211] op_sel_hi:[1,1,0]
	s_nop 0
	v_mov_b32_e32 v95, v0
	s_or_b64 exec, exec, s[22:23]
	s_waitcnt lgkmcnt(0)
	ds_bpermute_b32 v1, v45, v92
	s_and_saveexec_b64 s[22:23], s[100:101]
	v_mov_b32_e32 v0, v92
	s_waitcnt lgkmcnt(0)
	v_mul_f32_e32 v2, v59, v1
	v_xor_b32_e32 v210, v208, v2
	v_xor_b32_e32 v211, v208, v3
	v_pk_fma_f32 v[0:1], v[58:59], v[0:1], v[210:211] op_sel_hi:[1,1,0]
	s_nop 0
	v_mov_b32_e32 v92, v0
	s_or_b64 exec, exec, s[22:23]
	s_waitcnt lgkmcnt(0)
	ds_bpermute_b32 v1, v45, v93
	s_and_saveexec_b64 s[22:23], s[100:101]
	v_mov_b32_e32 v0, v93
	s_waitcnt lgkmcnt(0)
	v_mul_f32_e32 v2, v57, v1
	v_xor_b32_e32 v210, v208, v2
	v_xor_b32_e32 v211, v208, v3
	v_pk_fma_f32 v[0:1], v[56:57], v[0:1], v[210:211] op_sel_hi:[1,1,0]
	s_nop 0
	v_mov_b32_e32 v93, v0
	s_or_b64 exec, exec, s[22:23]
	s_waitcnt lgkmcnt(0)
	ds_bpermute_b32 v1, v45, v90
	s_and_saveexec_b64 s[22:23], s[100:101]
	v_mov_b32_e32 v0, v90
	s_waitcnt lgkmcnt(0)
	v_mul_f32_e32 v2, v63, v1
	v_xor_b32_e32 v210, v208, v2
	v_xor_b32_e32 v211, v208, v3
	v_pk_fma_f32 v[0:1], v[62:63], v[0:1], v[210:211] op_sel_hi:[1,1,0]
	s_nop 0
	v_mov_b32_e32 v90, v0
	s_or_b64 exec, exec, s[22:23]
	s_waitcnt lgkmcnt(0)
	ds_bpermute_b32 v1, v45, v91
	s_and_saveexec_b64 s[22:23], s[100:101]
	v_mov_b32_e32 v0, v91
	s_waitcnt lgkmcnt(0)
	v_mul_f32_e32 v2, v61, v1
	v_xor_b32_e32 v210, v208, v2
	v_xor_b32_e32 v211, v208, v3
	v_pk_fma_f32 v[0:1], v[60:61], v[0:1], v[210:211] op_sel_hi:[1,1,0]
	s_nop 0
	v_mov_b32_e32 v91, v0
	s_or_b64 exec, exec, s[22:23]
	s_waitcnt lgkmcnt(0)
	ds_bpermute_b32 v1, v45, v88
	s_and_saveexec_b64 s[22:23], s[100:101]
	v_mov_b32_e32 v0, v88
	s_waitcnt lgkmcnt(0)
	v_mul_f32_e32 v2, v67, v1
	v_xor_b32_e32 v210, v208, v2
	v_xor_b32_e32 v211, v208, v3
	v_pk_fma_f32 v[0:1], v[66:67], v[0:1], v[210:211] op_sel_hi:[1,1,0]
	s_nop 0
	v_mov_b32_e32 v88, v0
	s_or_b64 exec, exec, s[22:23]
	s_waitcnt lgkmcnt(0)
	ds_bpermute_b32 v1, v45, v89
	s_and_saveexec_b64 s[22:23], s[100:101]
	v_mov_b32_e32 v0, v89
	s_waitcnt lgkmcnt(0)
	v_mul_f32_e32 v2, v65, v1
	v_xor_b32_e32 v210, v208, v2
	v_xor_b32_e32 v211, v208, v3
	v_pk_fma_f32 v[0:1], v[64:65], v[0:1], v[210:211] op_sel_hi:[1,1,0]
	s_nop 0
	v_mov_b32_e32 v89, v0
	s_or_b64 exec, exec, s[22:23]
	s_waitcnt lgkmcnt(0)
	ds_bpermute_b32 v1, v45, v86
	s_and_saveexec_b64 s[22:23], s[100:101]
	v_mov_b32_e32 v0, v86
	s_waitcnt lgkmcnt(0)
	v_mul_f32_e32 v2, v71, v1
	v_xor_b32_e32 v210, v208, v2
	v_xor_b32_e32 v211, v208, v3
	v_pk_fma_f32 v[0:1], v[70:71], v[0:1], v[210:211] op_sel_hi:[1,1,0]
	s_nop 0
	v_mov_b32_e32 v86, v0
	s_or_b64 exec, exec, s[22:23]
	s_waitcnt lgkmcnt(0)
	ds_bpermute_b32 v1, v45, v87
	s_and_saveexec_b64 s[22:23], s[100:101]
	v_mov_b32_e32 v0, v87
	s_waitcnt lgkmcnt(0)
	v_mul_f32_e32 v2, v69, v1
	v_xor_b32_e32 v210, v208, v2
	v_xor_b32_e32 v211, v208, v3
	v_pk_fma_f32 v[0:1], v[68:69], v[0:1], v[210:211] op_sel_hi:[1,1,0]
	s_nop 0
	v_mov_b32_e32 v87, v0
	s_or_b64 exec, exec, s[22:23]
	s_waitcnt lgkmcnt(0)
	ds_bpermute_b32 v1, v45, v84
	s_and_saveexec_b64 s[22:23], s[100:101]
	v_mov_b32_e32 v0, v84
	s_waitcnt lgkmcnt(0)
	v_mul_f32_e32 v2, v75, v1
	v_xor_b32_e32 v210, v208, v2
	v_xor_b32_e32 v211, v208, v3
	v_pk_fma_f32 v[0:1], v[74:75], v[0:1], v[210:211] op_sel_hi:[1,1,0]
	s_nop 0
	v_mov_b32_e32 v84, v0
	s_or_b64 exec, exec, s[22:23]
	s_waitcnt lgkmcnt(0)
	ds_bpermute_b32 v1, v45, v85
	s_and_saveexec_b64 s[22:23], s[100:101]
	v_mov_b32_e32 v0, v85
	s_waitcnt lgkmcnt(0)
	v_mul_f32_e32 v2, v73, v1
	v_xor_b32_e32 v210, v208, v2
	v_xor_b32_e32 v211, v208, v3
	v_pk_fma_f32 v[0:1], v[72:73], v[0:1], v[210:211] op_sel_hi:[1,1,0]
	s_nop 0
	v_mov_b32_e32 v85, v0
	s_or_b64 exec, exec, s[22:23]
	s_waitcnt lgkmcnt(0)
	ds_bpermute_b32 v1, v45, v82
	s_and_saveexec_b64 s[22:23], s[100:101]
	v_mov_b32_e32 v0, v82
	s_waitcnt lgkmcnt(0)
	v_mul_f32_e32 v2, v79, v1
	v_xor_b32_e32 v210, v208, v2
	v_xor_b32_e32 v211, v208, v3
	v_pk_fma_f32 v[0:1], v[78:79], v[0:1], v[210:211] op_sel_hi:[1,1,0]
	s_nop 0
	v_mov_b32_e32 v82, v0
	s_or_b64 exec, exec, s[22:23]
	s_waitcnt lgkmcnt(0)
	ds_bpermute_b32 v1, v45, v83
	v_cmp_lt_i32_e64 s[0:1], 0, v16
	s_and_saveexec_b64 s[22:23], s[0:1]
	s_xor_b64 s[22:23], exec, s[22:23]
	s_cbranch_execz .LBB0_937
	v_cmp_eq_u32_e64 s[0:1], 1, v16
	s_and_saveexec_b64 s[24:25], s[0:1]
	s_cbranch_execz .LBB0_837
	v_mov_b32_e32 v0, v83
	s_waitcnt lgkmcnt(0)
	v_mul_f32_e32 v2, v77, v1
	v_pk_fma_f32 v[0:1], v[76:77], v[0:1], v[2:3] op_sel_hi:[1,1,0]
	s_nop 0
	v_mov_b32_e32 v83, v0

.LBB0_846:
	s_or_b64 exec, exec, s[0:1]
	ds_bpermute_b32 v63, v45, v1
	v_mov_b32_e32 v0, v60
	s_waitcnt lgkmcnt(1)
	ds_read_b64 v[60:61], v108 offset:136
	s_and_saveexec_b64 s[22:23], s[100:101]
	v_mov_b32_e32 v64, v1
	s_waitcnt lgkmcnt(0)
	v_mov_b32_e32 v65, v61
	v_mov_b32_e32 v62, v60
	v_mul_f32_e32 v66, v1, v60
	v_xor_b32_e32 v210, v208, v64
	v_xor_b32_e32 v211, v208, v65
	v_pk_fma_f32 v[62:63], v[210:211], v[62:63], v[66:67] op_sel_hi:[1,1,0]
	s_nop 0
	v_mov_b32_e32 v1, v63
	s_or_b64 exec, exec, s[22:23]
	s_waitcnt lgkmcnt(1)
	ds_bpermute_b32 v63, v45, v2
	ds_read_b64 v[64:65], v108 offset:144
	s_and_saveexec_b64 s[22:23], s[100:101]
	v_mov_b32_e32 v66, v2
	s_waitcnt lgkmcnt(0)
	v_mov_b32_e32 v67, v65
	v_mov_b32_e32 v62, v64
	v_mul_f32_e32 v2, v65, v63
	v_xor_b32_e32 v210, v208, v2
	v_xor_b32_e32 v211, v208, v3
	v_pk_fma_f32 v[62:63], v[66:67], v[62:63], v[210:211] op_sel_hi:[1,1,0]
	s_nop 0
	v_mov_b32_e32 v2, v62
	s_or_b64 exec, exec, s[22:23]
	ds_bpermute_b32 v67, v45, v3
	s_waitcnt lgkmcnt(2)
	ds_read_b64 v[62:63], v108 offset:152
	s_and_saveexec_b64 s[22:23], s[100:101]
	v_mov_b32_e32 v68, v3
	s_waitcnt lgkmcnt(0)
	v_mov_b32_e32 v69, v63
	v_mov_b32_e32 v66, v62
	v_mul_f32_e32 v70, v63, v67
	v_xor_b32_e32 v210, v208, v70
	v_xor_b32_e32 v211, v208, v71
	v_pk_fma_f32 v[66:67], v[68:69], v[66:67], v[210:211] op_sel_hi:[1,1,0]
	s_nop 0
	v_mov_b32_e32 v3, v66
	s_or_b64 exec, exec, s[22:23]
	s_waitcnt lgkmcnt(1)
	ds_bpermute_b32 v67, v45, v4
	ds_read_b64 v[68:69], v108 offset:160
	s_and_saveexec_b64 s[22:23], s[100:101]
	v_mov_b32_e32 v70, v4
	s_waitcnt lgkmcnt(0)
	v_mov_b32_e32 v71, v69
	v_mov_b32_e32 v66, v68
	v_mul_f32_e32 v4, v69, v67
	v_xor_b32_e32 v210, v208, v4
	v_xor_b32_e32 v211, v208, v5
	v_pk_fma_f32 v[66:67], v[70:71], v[66:67], v[210:211] op_sel_hi:[1,1,0]
	s_nop 0
	v_mov_b32_e32 v4, v66
	s_or_b64 exec, exec, s[22:23]
	ds_bpermute_b32 v71, v45, v5
	s_waitcnt lgkmcnt(2)
	ds_read_b64 v[66:67], v108 offset:168
	s_and_saveexec_b64 s[22:23], s[100:101]
	v_mov_b32_e32 v72, v5
	s_waitcnt lgkmcnt(0)
	v_mov_b32_e32 v73, v67
	v_mov_b32_e32 v70, v66
	v_mul_f32_e32 v74, v67, v71
	v_xor_b32_e32 v210, v208, v74
	v_xor_b32_e32 v211, v208, v75
	v_pk_fma_f32 v[70:71], v[72:73], v[70:71], v[210:211] op_sel_hi:[1,1,0]
	s_nop 0
	v_mov_b32_e32 v5, v70
	s_or_b64 exec, exec, s[22:23]
	s_waitcnt lgkmcnt(1)
	ds_bpermute_b32 v71, v45, v6
	ds_read_b64 v[72:73], v108 offset:176
	s_and_saveexec_b64 s[22:23], s[100:101]
	v_mov_b32_e32 v74, v6
	s_waitcnt lgkmcnt(0)
	v_mov_b32_e32 v75, v73
	v_mov_b32_e32 v70, v72
	v_mul_f32_e32 v6, v73, v71
	v_xor_b32_e32 v210, v208, v6
	v_xor_b32_e32 v211, v208, v7
	v_pk_fma_f32 v[70:71], v[74:75], v[70:71], v[210:211] op_sel_hi:[1,1,0]
	s_nop 0
	v_mov_b32_e32 v6, v70
	s_or_b64 exec, exec, s[22:23]
	ds_bpermute_b32 v75, v45, v7
	s_waitcnt lgkmcnt(2)
	ds_read_b64 v[70:71], v108 offset:184
	s_and_saveexec_b64 s[22:23], s[100:101]
	v_mov_b32_e32 v76, v7
	s_waitcnt lgkmcnt(0)
	v_mov_b32_e32 v77, v71
	v_mov_b32_e32 v74, v70
	v_mul_f32_e32 v78, v71, v75
	v_xor_b32_e32 v210, v208, v78
	v_xor_b32_e32 v211, v208, v79
	v_pk_fma_f32 v[74:75], v[76:77], v[74:75], v[210:211] op_sel_hi:[1,1,0]
	s_nop 0
	v_mov_b32_e32 v7, v74
	s_or_b64 exec, exec, s[22:23]
	v_cvt_pk_bf16_f32 v0, v0, v1
	v_cvt_pk_bf16_f32 v1, v2, v3
	v_cvt_pk_bf16_f32 v2, v4, v5
	v_cvt_pk_bf16_f32 v3, v6, v7
	global_store_dwordx4 v[58:59], v[0:3], off
	s_nop 1
	v_lshlrev_b64 v[0:1], 7, v[42:43]
	v_lshl_add_u64 v[58:59], v[54:55], 0, v[0:1]
	v_mov_b32_e32 v0, 0
	v_mov_b32_e32 v1, v0
	v_mov_b32_e32 v2, v0
	v_mov_b32_e32 v3, v0
	v_mov_b32_e32 v4, v0
	v_mov_b32_e32 v5, v0
	v_mov_b32_e32 v6, v0
	v_mov_b32_e32 v7, v0
	s_and_saveexec_b64 s[0:1], s[4:5]
	s_cbranch_execz .LBB0_890
	v_mov_b32_e32 v4, v196
	v_mov_b32_e32 v5, v197
	v_mov_b32_e32 v6, v198
	v_mov_b32_e32 v7, v199
	v_lshlrev_b32_e32 v0, 16, v4
	v_and_b32_e32 v1, 0xffff0000, v4
	v_lshlrev_b32_e32 v2, 16, v5
	v_and_b32_e32 v3, 0xffff0000, v5
	v_lshlrev_b32_e32 v4, 16, v6
	v_and_b32_e32 v5, 0xffff0000, v6
	v_lshlrev_b32_e32 v6, 16, v7
	v_and_b32_e32 v7, 0xffff0000, v7
.LBB0_890:
	s_or_b64 exec, exec, s[0:1]
	s_waitcnt lgkmcnt(1)
	ds_bpermute_b32 v75, v45, v0
	s_and_saveexec_b64 s[22:23], s[100:101]
	v_mov_b32_e32 v74, v0
	s_waitcnt lgkmcnt(0)
	v_pk_mul_f32 v[56:57], v[56:57], v[74:75]
	s_nop 0
	v_xor_b32_e32 v210, v208, v57
	v_add_f32_e32 v0, v56, v210
	s_or_b64 exec, exec, s[22:23]
	ds_bpermute_b32 v57, v45, v1
	s_and_saveexec_b64 s[22:23], s[100:101]
	v_mov_b32_e32 v56, v1
	v_mul_f32_e32 v74, v60, v1
	s_waitcnt lgkmcnt(0)
	v_xor_b32_e32 v210, v208, v60
	v_xor_b32_e32 v211, v208, v61
	v_pk_fma_f32 v[56:57], v[210:211], v[56:57], v[74:75] op_sel_hi:[1,1,0]
	s_nop 0
	v_mov_b32_e32 v1, v57
	s_or_b64 exec, exec, s[22:23]
	s_waitcnt lgkmcnt(0)
	ds_bpermute_b32 v57, v45, v2
	s_and_saveexec_b64 s[22:23], s[100:101]
	v_mov_b32_e32 v56, v2
	s_waitcnt lgkmcnt(0)
	v_mul_f32_e32 v2, v65, v57
	v_xor_b32_e32 v210, v208, v2
	v_xor_b32_e32 v211, v208, v3
	v_pk_fma_f32 v[56:57], v[64:65], v[56:57], v[210:211] op_sel_hi:[1,1,0]
	s_nop 0
	v_mov_b32_e32 v2, v56
	s_or_b64 exec, exec, s[22:23]
	s_waitcnt lgkmcnt(0)
	ds_bpermute_b32 v57, v45, v3
	s_and_saveexec_b64 s[22:23], s[100:101]
	v_mov_b32_e32 v56, v3
	s_waitcnt lgkmcnt(0)
	v_mul_f32_e32 v60, v63, v57
	v_xor_b32_e32 v210, v208, v60
	v_xor_b32_e32 v211, v208, v61
	v_pk_fma_f32 v[56:57], v[62:63], v[56:57], v[210:211] op_sel_hi:[1,1,0]
	s_nop 0
	v_mov_b32_e32 v3, v56
	s_or_b64 exec, exec, s[22:23]
	s_waitcnt lgkmcnt(0)
	ds_bpermute_b32 v57, v45, v4
	s_and_saveexec_b64 s[22:23], s[100:101]
	v_mov_b32_e32 v56, v4
	s_waitcnt lgkmcnt(0)
	v_mul_f32_e32 v4, v69, v57
	v_xor_b32_e32 v210, v208, v4
	v_xor_b32_e32 v211, v208, v5
	v_pk_fma_f32 v[56:57], v[68:69], v[56:57], v[210:211] op_sel_hi:[1,1,0]
	s_nop 0
	v_mov_b32_e32 v4, v56
	s_or_b64 exec, exec, s[22:23]
	s_waitcnt lgkmcnt(0)
	ds_bpermute_b32 v57, v45, v5
	s_and_saveexec_b64 s[22:23], s[100:101]
	v_mov_b32_e32 v56, v5
	s_waitcnt lgkmcnt(0)
	v_mul_f32_e32 v60, v67, v57
	v_xor_b32_e32 v210, v208, v60
	v_xor_b32_e32 v211, v208, v61
	v_pk_fma_f32 v[56:57], v[66:67], v[56:57], v[210:211] op_sel_hi:[1,1,0]
	s_nop 0
	v_mov_b32_e32 v5, v56
	s_or_b64 exec, exec, s[22:23]
	s_waitcnt lgkmcnt(0)
	ds_bpermute_b32 v57, v45, v6
	s_and_saveexec_b64 s[22:23], s[100:101]
	v_mov_b32_e32 v56, v6
	s_waitcnt lgkmcnt(0)
	v_mul_f32_e32 v6, v73, v57
	v_xor_b32_e32 v210, v208, v6
	v_xor_b32_e32 v211, v208, v7
	v_pk_fma_f32 v[56:57], v[72:73], v[56:57], v[210:211] op_sel_hi:[1,1,0]
	s_nop 0
	v_mov_b32_e32 v6, v56
	s_or_b64 exec, exec, s[22:23]
	s_waitcnt lgkmcnt(0)
	ds_bpermute_b32 v57, v45, v7
	v_cmp_lt_i32_e64 s[0:1], 0, v16
	s_and_saveexec_b64 s[22:23], s[0:1]
	s_xor_b64 s[22:23], exec, s[22:23]
	s_cbranch_execz .LBB0_939
	v_cmp_eq_u32_e64 s[0:1], 1, v16
	s_and_saveexec_b64 s[24:25], s[0:1]
	s_cbranch_execz .LBB0_935
	v_mov_b32_e32 v56, v7
	s_waitcnt lgkmcnt(0)
	v_mul_f32_e32 v60, v71, v57
	v_pk_fma_f32 v[56:57], v[70:71], v[56:57], v[60:61] op_sel_hi:[1,1,0]
	s_nop 0
	v_mov_b32_e32 v7, v56
